# v4 = v3 + accumulator zero-init with v_mov_b64 (half the VALU ops) in all six GEMM tile loops
# speedup vs baseline: 1.0149x; 1.0020x over previous
; template <class Epi, class Sched, bool ALIGN_EPI = false>
; __device__ __forceinline__ void gemm_phase8(PG8_LAS unsigned char* lds, const Gemm g, const Sched& S, const Epi& E) {
;     ...
;         const bool has_next = S.next(ui + 1, nxt);
;         const size_t nko = (has_next && nxt.kp > 0) ? (size_t)nxt.kp * g.kpiece : 0;
;         const char* nA = has_next ? (const char*)g.A + (size_t)nxt.pm * tstepA + (size_t)nxt.pn * astep + nko : cA; const char* nB = has_next ? (const char*)g.Bt + (size_t)nxt.pn * tstepB + nko : cB;
;         const int nt = (cur.kp < 0 ? g.K : g.kpiece) / 128;
;     ...
; #pragma unroll
;         for (int a = 0; a < 2; ++a)
; #pragma unroll
;             for (int b = 0; b < 2; ++b)
; #pragma unroll
;                 for (int m = 0; m < 4; ++m)
; #pragma unroll
;                     for (int n = 0; n < 2; ++n) acc[a][b][m][n] = (f32x4){0.f, 0.f, 0.f, 0.f};
.LBB0_324:
	s_ashr_i32 s15, s14, 31
	s_lshl_b64 s[16:17], s[14:15], 19
	s_add_u32 s16, s28, s16
	s_addc_u32 s17, s29, s17
	s_and_b64 s[18:19], s[2:3], exec
	s_cselect_b32 s15, s17, s23
	s_cselect_b32 s61, s16, s22
	s_ashr_i32 s13, s12, 31
	s_lshl_b64 s[18:19], s[12:13], 19
	s_add_u32 s18, s4, s18
	s_addc_u32 s19, s5, s19
	s_and_b64 s[26:27], s[2:3], exec
	s_cselect_b32 s13, s19, s25
	s_cselect_b32 s62, s18, s24
	s_add_u32 s22, s22, 0x40080
	s_addc_u32 s23, s23, 0
	s_add_u32 s63, s24, 0x100
	v_mov_b32_e32 v34, 0
	s_addc_u32 s64, s25, 0
	s_mov_b32 s65, -2
	v_mov_b32_e32 v35, v34
	v_mov_b64_e32 v[36:37], 0
	v_mov_b64_e32 v[38:39], 0
	v_mov_b64_e32 v[40:41], 0
	v_mov_b64_e32 v[42:43], 0
	v_mov_b64_e32 v[44:45], 0
	v_mov_b64_e32 v[46:47], 0
	v_mov_b64_e32 v[48:49], 0
	v_mov_b64_e32 v[50:51], 0
	v_mov_b64_e32 v[52:53], 0
	v_mov_b64_e32 v[54:55], 0
	v_mov_b64_e32 v[56:57], 0
	v_mov_b64_e32 v[58:59], 0
	v_mov_b64_e32 v[60:61], 0
	v_mov_b64_e32 v[62:63], 0
	v_mov_b64_e32 v[64:65], 0
	v_mov_b64_e32 v[66:67], 0
	v_mov_b64_e32 v[68:69], 0
	v_mov_b64_e32 v[70:71], 0
	v_mov_b64_e32 v[72:73], 0
	v_mov_b64_e32 v[74:75], 0
	v_mov_b64_e32 v[76:77], 0
	v_mov_b64_e32 v[78:79], 0
	v_mov_b64_e32 v[80:81], 0
	v_mov_b64_e32 v[82:83], 0
	v_mov_b64_e32 v[84:85], 0
	v_mov_b64_e32 v[86:87], 0
	v_mov_b64_e32 v[88:89], 0
	v_mov_b64_e32 v[90:91], 0
	v_mov_b64_e32 v[92:93], 0
	v_mov_b64_e32 v[94:95], 0
	v_mov_b64_e32 v[96:97], 0
	v_mov_b64_e32 v[98:99], 0
	v_mov_b64_e32 v[100:101], 0
	v_mov_b64_e32 v[102:103], 0
	v_mov_b64_e32 v[104:105], 0
	v_mov_b64_e32 v[106:107], 0
	v_mov_b64_e32 v[108:109], 0
	v_mov_b64_e32 v[110:111], 0
	v_mov_b64_e32 v[112:113], 0
	v_mov_b64_e32 v[114:115], 0
	v_mov_b64_e32 v[116:117], 0
	v_mov_b64_e32 v[118:119], 0
	v_mov_b64_e32 v[120:121], 0
	v_mov_b64_e32 v[122:123], 0
	v_mov_b64_e32 v[124:125], 0
	v_mov_b64_e32 v[126:127], 0
	v_mov_b64_e32 v[128:129], 0
	v_mov_b64_e32 v[130:131], 0
	v_mov_b64_e32 v[132:133], 0
	v_mov_b64_e32 v[134:135], 0
	v_mov_b64_e32 v[136:137], 0
	v_mov_b64_e32 v[138:139], 0
	v_mov_b64_e32 v[140:141], 0
	v_mov_b64_e32 v[142:143], 0
	v_mov_b64_e32 v[144:145], 0
	v_mov_b64_e32 v[146:147], 0
	v_mov_b64_e32 v[148:149], 0
	v_mov_b64_e32 v[150:151], 0
	v_mov_b64_e32 v[152:153], 0
	v_mov_b64_e32 v[154:155], 0
	v_mov_b64_e32 v[156:157], 0
	v_mov_b64_e32 v[158:159], 0
	v_mov_b64_e32 v[160:161], 0

; template <class Epi, class Sched, bool ALIGN_EPI = false>
; __device__ __forceinline__ void gemm_phase8(PG8_LAS unsigned char* lds, const Gemm g, const Sched& S, const Epi& E) {
;     ...
;         const size_t nko = (has_next && nxt.kp > 0) ? (size_t)nxt.kp * g.kpiece : 0;
;         const char* nA = has_next ? (const char*)g.A + (size_t)nxt.pm * tstepA + (size_t)nxt.pn * astep + nko : cA; const char* nB = has_next ? (const char*)g.Bt + (size_t)nxt.pn * tstepB + nko : cB;
;         const int nt = (cur.kp < 0 ? g.K : g.kpiece) / 128;
;     ...
; #pragma unroll
;         for (int a = 0; a < 2; ++a)
; #pragma unroll
;             for (int b = 0; b < 2; ++b)
; #pragma unroll
;                 for (int m = 0; m < 4; ++m)
; #pragma unroll
;                     for (int n = 0; n < 2; ++n) acc[a][b][m][n] = (f32x4){0.f, 0.f, 0.f, 0.f};
.LBB0_501:
	s_cmp_gt_i32 s24, -1
	s_cselect_b64 s[26:27], -1, 0
	s_cmp_lt_i32 s24, 0
	s_cselect_b32 s25, 44, 4
	s_add_i32 s81, s25, -2
	s_add_u32 s28, s28, 0xb0080
	s_addc_u32 s29, s29, 0
	s_add_u32 s82, s30, 0x100
	v_mov_b32_e32 v34, 0
	s_mov_b32 s34, 0
	s_addc_u32 s83, s31, 0
	v_mov_b32_e32 v35, v34
	v_mov_b64_e32 v[36:37], 0
	v_mov_b64_e32 v[38:39], 0
	v_mov_b64_e32 v[40:41], 0
	v_mov_b64_e32 v[42:43], 0
	v_mov_b64_e32 v[44:45], 0
	v_mov_b64_e32 v[46:47], 0
	v_mov_b64_e32 v[48:49], 0
	v_mov_b64_e32 v[50:51], 0
	v_mov_b64_e32 v[52:53], 0
	v_mov_b64_e32 v[54:55], 0
	v_mov_b64_e32 v[56:57], 0
	v_mov_b64_e32 v[58:59], 0
	v_mov_b64_e32 v[60:61], 0
	v_mov_b64_e32 v[62:63], 0
	v_mov_b64_e32 v[64:65], 0
	v_mov_b64_e32 v[66:67], 0
	v_mov_b64_e32 v[68:69], 0
	v_mov_b64_e32 v[70:71], 0
	v_mov_b64_e32 v[72:73], 0
	v_mov_b64_e32 v[74:75], 0
	v_mov_b64_e32 v[76:77], 0
	v_mov_b64_e32 v[78:79], 0
	v_mov_b64_e32 v[80:81], 0
	v_mov_b64_e32 v[82:83], 0
	v_mov_b64_e32 v[84:85], 0
	v_mov_b64_e32 v[86:87], 0
	v_mov_b64_e32 v[88:89], 0
	v_mov_b64_e32 v[90:91], 0
	v_mov_b64_e32 v[92:93], 0
	v_mov_b64_e32 v[94:95], 0
	v_mov_b64_e32 v[96:97], 0
	v_mov_b64_e32 v[98:99], 0
	v_mov_b64_e32 v[100:101], 0
	v_mov_b64_e32 v[102:103], 0
	v_mov_b64_e32 v[104:105], 0
	v_mov_b64_e32 v[106:107], 0
	v_mov_b64_e32 v[108:109], 0
	v_mov_b64_e32 v[110:111], 0
	v_mov_b64_e32 v[112:113], 0
	v_mov_b64_e32 v[114:115], 0
	v_mov_b64_e32 v[116:117], 0
	v_mov_b64_e32 v[118:119], 0
	v_mov_b64_e32 v[120:121], 0
	v_mov_b64_e32 v[122:123], 0
	v_mov_b64_e32 v[124:125], 0
	v_mov_b64_e32 v[126:127], 0
	v_mov_b64_e32 v[128:129], 0
	v_mov_b64_e32 v[130:131], 0
	v_mov_b64_e32 v[132:133], 0
	v_mov_b64_e32 v[134:135], 0
	v_mov_b64_e32 v[136:137], 0
	v_mov_b64_e32 v[138:139], 0
	v_mov_b64_e32 v[140:141], 0
	v_mov_b64_e32 v[142:143], 0
	v_mov_b64_e32 v[144:145], 0
	v_mov_b64_e32 v[146:147], 0
	v_mov_b64_e32 v[148:149], 0
	v_mov_b64_e32 v[150:151], 0
	v_mov_b64_e32 v[152:153], 0
	v_mov_b64_e32 v[154:155], 0
	v_mov_b64_e32 v[156:157], 0
	v_mov_b64_e32 v[158:159], 0
	v_mov_b64_e32 v[160:161], 0

; template <class Epi, class Sched, bool ALIGN_EPI = false>
; __device__ __forceinline__ void gemm_phase(PG8_LAS unsigned char* lds, const Gemm g, const Sched& S, const Epi& E) {
;     ...
;         const bool has_next = S.next(ui + 1, nxt);
;         const size_t nko = (has_next && nxt.kp > 0) ? (size_t)nxt.kp * g.kpiece * 2 : 0;
;         const char* nA = has_next ? (const char*)g.A + (size_t)nxt.pm * tstepA + (size_t)nxt.pn * astep + nko : cA; const char* nB = has_next ? (const char*)g.Bt + (size_t)nxt.pn * tstepB + nko : cB;
;         const int nt = (cur.kp < 0 ? g.K : g.kpiece) / BK;
;     ...
; #pragma unroll
;         for (int a = 0; a < 2; ++a)
; #pragma unroll
;             for (int b = 0; b < 2; ++b)
; #pragma unroll
;                 for (int m = 0; m < 4; ++m)
; #pragma unroll
;                     for (int n = 0; n < 2; ++n) acc[a][b][m][n] = (f32x4){0.f, 0.f, 0.f, 0.f};
.LBB0_733:
	s_ashr_i32 s27, s26, 31
	s_lshl_b64 s[28:29], s[26:27], 20
	s_add_u32 s28, s56, s28
	s_addc_u32 s29, s57, s29
	s_and_b64 s[30:31], s[2:3], exec
	s_cselect_b32 s13, s29, s53
	s_cselect_b32 s27, s28, s52
	s_ashr_i32 s25, s24, 31
	s_lshl_b64 s[30:31], s[24:25], 20
	s_add_u32 s30, s4, s30
	s_addc_u32 s31, s5, s31
	s_and_b64 s[54:55], s[2:3], exec
	s_cselect_b32 s25, s31, s35
	s_cselect_b32 s82, s30, s34
	s_add_u32 s52, s52, 0x80080
	s_addc_u32 s53, s53, 0
	s_add_u32 s83, s34, 0x100
	v_mov_b32_e32 v2, 0
	s_addc_u32 s84, s35, 0
	s_mov_b32 s85, -2
	v_mov_b32_e32 v3, v2
	v_mov_b64_e32 v[4:5], 0
	v_mov_b64_e32 v[6:7], 0
	v_mov_b64_e32 v[8:9], 0
	v_mov_b64_e32 v[10:11], 0
	v_mov_b64_e32 v[12:13], 0
	v_mov_b64_e32 v[14:15], 0
	v_mov_b64_e32 v[16:17], 0
	v_mov_b64_e32 v[18:19], 0
	v_mov_b64_e32 v[20:21], 0
	v_mov_b64_e32 v[22:23], 0
	v_mov_b64_e32 v[24:25], 0
	v_mov_b64_e32 v[26:27], 0
	v_mov_b64_e32 v[28:29], 0
	v_mov_b64_e32 v[30:31], 0
	v_mov_b64_e32 v[32:33], 0
	v_mov_b64_e32 v[34:35], 0
	v_mov_b64_e32 v[36:37], 0
	v_mov_b64_e32 v[38:39], 0
	v_mov_b64_e32 v[40:41], 0
	v_mov_b64_e32 v[42:43], 0
	v_mov_b64_e32 v[44:45], 0
	v_mov_b64_e32 v[46:47], 0
	v_mov_b64_e32 v[48:49], 0
	v_mov_b64_e32 v[50:51], 0
	v_mov_b64_e32 v[52:53], 0
	v_mov_b64_e32 v[54:55], 0
	v_mov_b64_e32 v[56:57], 0
	v_mov_b64_e32 v[58:59], 0
	v_mov_b64_e32 v[60:61], 0
	v_mov_b64_e32 v[62:63], 0
	v_mov_b64_e32 v[64:65], 0
	v_mov_b64_e32 v[66:67], 0
	v_mov_b64_e32 v[68:69], 0
	v_mov_b64_e32 v[70:71], 0
	v_mov_b64_e32 v[72:73], 0
	v_mov_b64_e32 v[74:75], 0
	v_mov_b64_e32 v[76:77], 0
	v_mov_b64_e32 v[78:79], 0
	v_mov_b64_e32 v[80:81], 0
	v_mov_b64_e32 v[82:83], 0
	v_mov_b64_e32 v[84:85], 0
	v_mov_b64_e32 v[86:87], 0
	v_mov_b64_e32 v[88:89], 0
	v_mov_b64_e32 v[90:91], 0
	v_mov_b64_e32 v[92:93], 0
	v_mov_b64_e32 v[94:95], 0
	v_mov_b64_e32 v[96:97], 0
	v_mov_b64_e32 v[98:99], 0
	v_mov_b64_e32 v[100:101], 0
	v_mov_b64_e32 v[102:103], 0
	v_mov_b64_e32 v[104:105], 0
	v_mov_b64_e32 v[106:107], 0
	v_mov_b64_e32 v[108:109], 0
	v_mov_b64_e32 v[110:111], 0
	v_mov_b64_e32 v[112:113], 0
	v_mov_b64_e32 v[114:115], 0
	v_mov_b64_e32 v[116:117], 0
	v_mov_b64_e32 v[118:119], 0
	v_mov_b64_e32 v[120:121], 0
	v_mov_b64_e32 v[122:123], 0
	v_mov_b64_e32 v[124:125], 0
	v_mov_b64_e32 v[126:127], 0
	v_mov_b64_e32 v[128:129], 0

; template <class Epi, class Sched, bool ALIGN_EPI = false>
; __device__ __forceinline__ void gemm_phase8(PG8_LAS unsigned char* lds, const Gemm g, const Sched& S, const Epi& E) {
;     ...
;         const bool has_next = S.next(ui + 1, nxt);
;         const size_t nko = (has_next && nxt.kp > 0) ? (size_t)nxt.kp * g.kpiece : 0;
;         const char* nA = has_next ? (const char*)g.A + (size_t)nxt.pm * tstepA + (size_t)nxt.pn * astep + nko : cA; const char* nB = has_next ? (const char*)g.Bt + (size_t)nxt.pn * tstepB + nko : cB;
;         const int nt = (cur.kp < 0 ? g.K : g.kpiece) / 128;
;     ...
; #pragma unroll
;         for (int a = 0; a < 2; ++a)
; #pragma unroll
;             for (int b = 0; b < 2; ++b)
; #pragma unroll
;                 for (int m = 0; m < 4; ++m)
; #pragma unroll
;                     for (int n = 0; n < 2; ++n) acc[a][b][m][n] = (f32x4){0.f, 0.f, 0.f, 0.f};
.LBB0_1186:
	s_cmp_gt_i32 s0, 0
	s_cselect_b64 s[24:25], -1, 0
	s_and_b64 s[24:25], s[22:23], s[24:25]
	s_lshl_b64 s[26:27], s[0:1], 9
	s_and_b64 s[24:25], s[24:25], exec
	s_cselect_b32 s54, s27, 0
	s_cselect_b32 s55, s26, 0
	s_ashr_i32 s19, s18, 31
	s_lshl_b64 s[24:25], s[18:19], 19
	s_add_u32 s19, s33, s24
	s_addc_u32 s21, s60, s25
	s_add_u32 s24, s19, s55
	s_addc_u32 s25, s21, s54
	s_and_b64 s[26:27], s[22:23], exec
	s_cselect_b32 s19, s25, s57
	s_cselect_b32 s31, s24, s56
	s_ashr_i32 s21, s20, 31
	s_lshl_b64 s[26:27], s[20:21], 19
	s_add_u32 s21, s2, s26
	s_addc_u32 s27, s3, s27
	s_add_u32 s26, s21, s55
	s_addc_u32 s27, s27, s54
	s_and_b64 s[54:55], s[22:23], exec
	s_cselect_b32 s21, s27, s35
	s_cselect_b32 s75, s26, s34
	s_cmp_gt_i32 s30, -1
	s_cselect_b64 s[54:55], -1, 0
	s_cmp_lt_i32 s30, 0
	s_cselect_b32 s76, 16, 4
	s_add_i32 s77, s76, -2
	s_add_u32 s56, s56, 0x40080
	s_addc_u32 s57, s57, 0
	s_add_u32 s78, s34, 0x100
	v_mov_b32_e32 v34, 0
	s_mov_b32 s58, 0
	s_addc_u32 s79, s35, 0
	v_mov_b32_e32 v35, v34
	v_mov_b64_e32 v[36:37], 0
	v_mov_b64_e32 v[38:39], 0
	v_mov_b64_e32 v[40:41], 0
	v_mov_b64_e32 v[42:43], 0
	v_mov_b64_e32 v[44:45], 0
	v_mov_b64_e32 v[46:47], 0
	v_mov_b64_e32 v[48:49], 0
	v_mov_b64_e32 v[50:51], 0
	v_mov_b64_e32 v[52:53], 0
	v_mov_b64_e32 v[54:55], 0
	v_mov_b64_e32 v[56:57], 0
	v_mov_b64_e32 v[58:59], 0
	v_mov_b64_e32 v[60:61], 0
	v_mov_b64_e32 v[62:63], 0
	v_mov_b64_e32 v[64:65], 0
	v_mov_b64_e32 v[66:67], 0
	v_mov_b64_e32 v[68:69], 0
	v_mov_b64_e32 v[70:71], 0
	v_mov_b64_e32 v[72:73], 0
	v_mov_b64_e32 v[74:75], 0
	v_mov_b64_e32 v[76:77], 0
	v_mov_b64_e32 v[78:79], 0
	v_mov_b64_e32 v[80:81], 0
	v_mov_b64_e32 v[82:83], 0
	v_mov_b64_e32 v[84:85], 0
	v_mov_b64_e32 v[86:87], 0
	v_mov_b64_e32 v[88:89], 0
	v_mov_b64_e32 v[90:91], 0
	v_mov_b64_e32 v[92:93], 0
	v_mov_b64_e32 v[94:95], 0
	v_mov_b64_e32 v[96:97], 0
	v_mov_b64_e32 v[98:99], 0
	v_mov_b64_e32 v[100:101], 0
	v_mov_b64_e32 v[102:103], 0
	v_mov_b64_e32 v[104:105], 0
	v_mov_b64_e32 v[106:107], 0
	v_mov_b64_e32 v[108:109], 0
	v_mov_b64_e32 v[110:111], 0
	v_mov_b64_e32 v[112:113], 0
	v_mov_b64_e32 v[114:115], 0
	v_mov_b64_e32 v[116:117], 0
	v_mov_b64_e32 v[118:119], 0
	v_mov_b64_e32 v[120:121], 0
	v_mov_b64_e32 v[122:123], 0
	v_mov_b64_e32 v[124:125], 0
	v_mov_b64_e32 v[126:127], 0
	v_mov_b64_e32 v[128:129], 0
	v_mov_b64_e32 v[130:131], 0
	v_mov_b64_e32 v[132:133], 0
	v_mov_b64_e32 v[134:135], 0
	v_mov_b64_e32 v[136:137], 0
	v_mov_b64_e32 v[138:139], 0
	v_mov_b64_e32 v[140:141], 0
	v_mov_b64_e32 v[142:143], 0
	v_mov_b64_e32 v[144:145], 0
	v_mov_b64_e32 v[146:147], 0
	v_mov_b64_e32 v[148:149], 0
	v_mov_b64_e32 v[150:151], 0
	v_mov_b64_e32 v[152:153], 0
	v_mov_b64_e32 v[154:155], 0
	v_mov_b64_e32 v[156:157], 0
	v_mov_b64_e32 v[158:159], 0
	v_mov_b64_e32 v[160:161], 0

; template <class Epi, class Sched, bool ALIGN_EPI = false>
; __device__ __forceinline__ void gemm_phase8(PG8_LAS unsigned char* lds, const Gemm g, const Sched& S, const Epi& E) {
;     ...
;         const bool has_next = S.next(ui + 1, nxt);
;         const size_t nko = (has_next && nxt.kp > 0) ? (size_t)nxt.kp * g.kpiece : 0;
;         const char* nA = has_next ? (const char*)g.A + (size_t)nxt.pm * tstepA + (size_t)nxt.pn * astep + nko : cA; const char* nB = has_next ? (const char*)g.Bt + (size_t)nxt.pn * tstepB + nko : cB;
;         const int nt = (cur.kp < 0 ? g.K : g.kpiece) / 128;
;     ...
; #pragma unroll
;         for (int a = 0; a < 2; ++a)
; #pragma unroll
;             for (int b = 0; b < 2; ++b)
; #pragma unroll
;                 for (int m = 0; m < 4; ++m)
; #pragma unroll
;                     for (int n = 0; n < 2; ++n) acc[a][b][m][n] = (f32x4){0.f, 0.f, 0.f, 0.f};
.LBB0_1421:
	s_ashr_i32 s13, s12, 31
	s_lshl_b64 s[14:15], s[12:13], 19
	s_add_u32 s14, s26, s14
	s_addc_u32 s15, s27, s15
	s_and_b64 s[16:17], s[2:3], exec
	s_cselect_b32 s13, s15, s21
	s_cselect_b32 s45, s14, s20
	s_ashr_i32 s11, s10, 31
	s_lshl_b64 s[16:17], s[10:11], 19
	s_add_u32 s16, s28, s16
	s_addc_u32 s17, s29, s17
	s_and_b64 s[24:25], s[2:3], exec
	s_cselect_b32 s11, s17, s23
	s_cselect_b32 s52, s16, s22
	s_add_u32 s20, s20, 0x40080
	s_addc_u32 s21, s21, 0
	s_add_u32 s53, s22, 0x100
	v_mov_b32_e32 v34, 0
	s_addc_u32 s54, s23, 0
	s_mov_b32 s55, -2
	v_mov_b32_e32 v35, v34
	v_mov_b64_e32 v[36:37], 0
	v_mov_b64_e32 v[38:39], 0
	v_mov_b64_e32 v[40:41], 0
	v_mov_b64_e32 v[42:43], 0
	v_mov_b64_e32 v[44:45], 0
	v_mov_b64_e32 v[46:47], 0
	v_mov_b64_e32 v[48:49], 0
	v_mov_b64_e32 v[50:51], 0
	v_mov_b64_e32 v[52:53], 0
	v_mov_b64_e32 v[54:55], 0
	v_mov_b64_e32 v[56:57], 0
	v_mov_b64_e32 v[58:59], 0
	v_mov_b64_e32 v[60:61], 0
	v_mov_b64_e32 v[62:63], 0
	v_mov_b64_e32 v[64:65], 0
	v_mov_b64_e32 v[66:67], 0
	v_mov_b64_e32 v[68:69], 0
	v_mov_b64_e32 v[70:71], 0
	v_mov_b64_e32 v[72:73], 0
	v_mov_b64_e32 v[74:75], 0
	v_mov_b64_e32 v[76:77], 0
	v_mov_b64_e32 v[78:79], 0
	v_mov_b64_e32 v[80:81], 0
	v_mov_b64_e32 v[82:83], 0
	v_mov_b64_e32 v[84:85], 0
	v_mov_b64_e32 v[86:87], 0
	v_mov_b64_e32 v[88:89], 0
	v_mov_b64_e32 v[90:91], 0
	v_mov_b64_e32 v[92:93], 0
	v_mov_b64_e32 v[94:95], 0
	v_mov_b64_e32 v[96:97], 0
	v_mov_b64_e32 v[98:99], 0
	v_mov_b64_e32 v[100:101], 0
	v_mov_b64_e32 v[102:103], 0
	v_mov_b64_e32 v[104:105], 0
	v_mov_b64_e32 v[106:107], 0
	v_mov_b64_e32 v[108:109], 0
	v_mov_b64_e32 v[110:111], 0
	v_mov_b64_e32 v[112:113], 0
	v_mov_b64_e32 v[114:115], 0
	v_mov_b64_e32 v[116:117], 0
	v_mov_b64_e32 v[118:119], 0
	v_mov_b64_e32 v[120:121], 0
	v_mov_b64_e32 v[122:123], 0
	v_mov_b64_e32 v[124:125], 0
	v_mov_b64_e32 v[126:127], 0
	v_mov_b64_e32 v[128:129], 0
	v_mov_b64_e32 v[130:131], 0
	v_mov_b64_e32 v[132:133], 0
	v_mov_b64_e32 v[134:135], 0
	v_mov_b64_e32 v[136:137], 0
	v_mov_b64_e32 v[138:139], 0
	v_mov_b64_e32 v[140:141], 0
	v_mov_b64_e32 v[142:143], 0
	v_mov_b64_e32 v[144:145], 0
	v_mov_b64_e32 v[146:147], 0
	v_mov_b64_e32 v[148:149], 0
	v_mov_b64_e32 v[150:151], 0
	v_mov_b64_e32 v[152:153], 0
	v_mov_b64_e32 v[154:155], 0
	v_mov_b64_e32 v[156:157], 0
	v_mov_b64_e32 v[158:159], 0
	v_mov_b64_e32 v[160:161], 0

; template <class Epi, class Sched, bool ALIGN_EPI = false>
; __device__ __forceinline__ void gemm_phase8(PG8_LAS unsigned char* lds, const Gemm g, const Sched& S, const Epi& E) {
;     ...
;         const size_t nko = (has_next && nxt.kp > 0) ? (size_t)nxt.kp * g.kpiece : 0;
;         const char* nA = has_next ? (const char*)g.A + (size_t)nxt.pm * tstepA + (size_t)nxt.pn * astep + nko : cA; const char* nB = has_next ? (const char*)g.Bt + (size_t)nxt.pn * tstepB + nko : cB;
;         const int nt = (cur.kp < 0 ? g.K : g.kpiece) / 128;
;     ...
; #pragma unroll
;         for (int a = 0; a < 2; ++a)
; #pragma unroll
;             for (int b = 0; b < 2; ++b)
; #pragma unroll
;                 for (int m = 0; m < 4; ++m)
; #pragma unroll
;                     for (int n = 0; n < 2; ++n) acc[a][b][m][n] = (f32x4){0.f, 0.f, 0.f, 0.f};
.LBB0_1510:
	s_cmp_gt_i32 s30, -1
	s_cselect_b64 s[36:37], -1, 0
	s_cmp_lt_i32 s30, 0
	s_cselect_b32 s31, 44, 4
	s_add_i32 s79, s31, -2
	s_add_u32 s38, s38, 0xb0080
	s_addc_u32 s39, s39, 0
	s_add_u32 s80, s34, 0x100
	v_mov_b32_e32 v34, 0
	s_mov_b32 s40, 0
	s_addc_u32 s81, s35, 0
	v_mov_b32_e32 v35, v34
	v_mov_b64_e32 v[36:37], 0
	v_mov_b64_e32 v[38:39], 0
	v_mov_b64_e32 v[40:41], 0
	v_mov_b64_e32 v[42:43], 0
	v_mov_b64_e32 v[44:45], 0
	v_mov_b64_e32 v[46:47], 0
	v_mov_b64_e32 v[48:49], 0
	v_mov_b64_e32 v[50:51], 0
	v_mov_b64_e32 v[52:53], 0
	v_mov_b64_e32 v[54:55], 0
	v_mov_b64_e32 v[56:57], 0
	v_mov_b64_e32 v[58:59], 0
	v_mov_b64_e32 v[60:61], 0
	v_mov_b64_e32 v[62:63], 0
	v_mov_b64_e32 v[64:65], 0
	v_mov_b64_e32 v[66:67], 0
	v_mov_b64_e32 v[68:69], 0
	v_mov_b64_e32 v[70:71], 0
	v_mov_b64_e32 v[72:73], 0
	v_mov_b64_e32 v[74:75], 0
	v_mov_b64_e32 v[76:77], 0
	v_mov_b64_e32 v[78:79], 0
	v_mov_b64_e32 v[80:81], 0
	v_mov_b64_e32 v[82:83], 0
	v_mov_b64_e32 v[84:85], 0
	v_mov_b64_e32 v[86:87], 0
	v_mov_b64_e32 v[88:89], 0
	v_mov_b64_e32 v[90:91], 0
	v_mov_b64_e32 v[92:93], 0
	v_mov_b64_e32 v[94:95], 0
	v_mov_b64_e32 v[96:97], 0
	v_mov_b64_e32 v[98:99], 0
	v_mov_b64_e32 v[100:101], 0
	v_mov_b64_e32 v[102:103], 0
	v_mov_b64_e32 v[104:105], 0
	v_mov_b64_e32 v[106:107], 0
	v_mov_b64_e32 v[108:109], 0
	v_mov_b64_e32 v[110:111], 0
	v_mov_b64_e32 v[112:113], 0
	v_mov_b64_e32 v[114:115], 0
	v_mov_b64_e32 v[116:117], 0
	v_mov_b64_e32 v[118:119], 0
	v_mov_b64_e32 v[120:121], 0
	v_mov_b64_e32 v[122:123], 0
	v_mov_b64_e32 v[124:125], 0
	v_mov_b64_e32 v[126:127], 0
	v_mov_b64_e32 v[128:129], 0
	v_mov_b64_e32 v[130:131], 0
	v_mov_b64_e32 v[132:133], 0
	v_mov_b64_e32 v[134:135], 0
	v_mov_b64_e32 v[136:137], 0
	v_mov_b64_e32 v[138:139], 0
	v_mov_b64_e32 v[140:141], 0
	v_mov_b64_e32 v[142:143], 0
	v_mov_b64_e32 v[144:145], 0
	v_mov_b64_e32 v[146:147], 0
	v_mov_b64_e32 v[148:149], 0
	v_mov_b64_e32 v[150:151], 0
	v_mov_b64_e32 v[152:153], 0
	v_mov_b64_e32 v[154:155], 0
	v_mov_b64_e32 v[156:157], 0
	v_mov_b64_e32 v[158:159], 0
	v_mov_b64_e32 v[160:161], 0
